# v37 + phase-B norm output stores write-through (sc0 sc1) to pre-drain L2 before the grid barrier
# baseline (speedup 1.0000x reference)
.LBB0_142:
	global_load_dwordx4 v[92:95], v[82:83], off offset:-4096 nt
	global_load_dwordx4 v[96:99], v[82:83], off offset:-3072 nt
	global_load_dwordx4 v[100:103], v[82:83], off offset:-2048 nt
	global_load_dwordx4 v[104:107], v[82:83], off offset:-1024 nt
	global_load_dwordx4 v[108:111], v[82:83], off nt
	global_load_dwordx4 v[112:115], v[82:83], off offset:1024 nt
	global_load_dwordx4 v[116:119], v[82:83], off offset:2048 nt
	global_load_dwordx4 v[32:35], v[82:83], off offset:3072 nt
	global_load_dwordx4 v[120:123], v[38:39], off
	v_add_u32_e32 v126, 0x4000, v36
	v_ashrrev_i32_e32 v127, 31, v126
	v_lshlrev_b64 v[126:127], 12, v[126:127]
	v_lshl_add_u64 v[126:127], v[80:81], 0, v[126:127]
	v_add_u32_e32 v36, s6, v36
	v_lshl_add_u64 v[82:83], v[82:83], 0, s[8:9]
	s_waitcnt vmcnt(8)
	v_mul_f32_e32 v91, v93, v93
	s_waitcnt vmcnt(7)
	v_mul_f32_e32 v124, v97, v97
	s_waitcnt vmcnt(6)
	v_mul_f32_e32 v145, v101, v101
	v_fmac_f32_e32 v91, v92, v92
	v_fmac_f32_e32 v124, v96, v96
	s_waitcnt vmcnt(5)
	v_mul_f32_e32 v146, v105, v105
	s_waitcnt vmcnt(4)
	v_mov_b32_e32 v130, v109
	s_waitcnt vmcnt(3)
	v_mov_b32_e32 v131, v113
	v_fmac_f32_e32 v145, v100, v100
	v_fmac_f32_e32 v91, v94, v94
	v_fmac_f32_e32 v124, v98, v98
	v_mov_b32_e32 v128, v108
	v_mov_b32_e32 v129, v112
	v_fmac_f32_e32 v146, v104, v104
	v_pk_mul_f32 v[130:131], v[130:131], v[130:131]
	v_fmac_f32_e32 v145, v102, v102
	v_fmac_f32_e32 v91, v95, v95
	v_fmac_f32_e32 v124, v99, v99
	v_mov_b32_e32 v132, v110
	v_mov_b32_e32 v133, v114
	s_waitcnt vmcnt(2)
	v_mov_b32_e32 v138, v117
	s_waitcnt vmcnt(1)
	v_mov_b32_e32 v139, v33
	v_fmac_f32_e32 v146, v106, v106
	v_pk_fma_f32 v[128:129], v[128:129], v[128:129], v[130:131]
	v_fmac_f32_e32 v145, v103, v103
	v_add_f32_e32 v91, v91, v124
	v_mov_b32_e32 v134, v111
	v_mov_b32_e32 v135, v115
	v_mov_b32_e32 v136, v116
	v_mov_b32_e32 v137, v32
	v_pk_mul_f32 v[138:139], v[138:139], v[138:139]
	v_fmac_f32_e32 v146, v107, v107
	v_pk_fma_f32 v[128:129], v[132:133], v[132:133], v[128:129]
	v_add_f32_e32 v91, v91, v145
	v_mov_b32_e32 v140, v118
	v_mov_b32_e32 v141, v34
	v_pk_fma_f32 v[130:131], v[136:137], v[136:137], v[138:139]
	v_pk_fma_f32 v[128:129], v[134:135], v[134:135], v[128:129]
	v_add_f32_e32 v91, v91, v146
	v_mov_b32_e32 v142, v119
	v_mov_b32_e32 v143, v35
	v_pk_fma_f32 v[130:131], v[140:141], v[140:141], v[130:131]
	v_add_f32_e32 v91, v91, v128
	v_pk_fma_f32 v[130:131], v[142:143], v[142:143], v[130:131]
	v_add_f32_e32 v91, v91, v129
	v_add_f32_e32 v91, v91, v130
	v_add_f32_e32 v91, v91, v131
	ds_bpermute_b32 v124, v84, v91
	s_waitcnt lgkmcnt(0)
	v_add_f32_e32 v91, v91, v124
	ds_bpermute_b32 v124, v86, v91
	s_waitcnt lgkmcnt(0)
	v_add_f32_e32 v91, v91, v124
	ds_bpermute_b32 v124, v87, v91
	s_waitcnt lgkmcnt(0)
	v_add_f32_e32 v91, v91, v124
	ds_bpermute_b32 v124, v88, v91
	s_waitcnt lgkmcnt(0)
	v_add_f32_e32 v91, v91, v124
	ds_bpermute_b32 v124, v89, v91
	s_waitcnt lgkmcnt(0)
	v_add_f32_e32 v91, v91, v124
	ds_bpermute_b32 v124, v90, v91
	s_waitcnt lgkmcnt(0)
	v_add_f32_e32 v91, v91, v124
	v_fmamk_f32 v91, v91, 0x3a000000, v37
	v_mul_f32_e32 v124, 0x4b800000, v91
	v_cmp_gt_f32_e32 vcc, s2, v91
	s_nop 1
	v_cndmask_b32_e32 v91, v91, v124, vcc
	v_rsq_f32_e32 v91, v91
	s_nop 0
	v_mul_f32_e32 v124, 0x45800000, v91
	v_cndmask_b32_e32 v124, v91, v124, vcc
	v_pk_mul_f32 v[92:93], v[92:93], v[124:125] op_sel_hi:[1,0]
	v_pk_mul_f32 v[94:95], v[94:95], v[124:125] op_sel_hi:[1,0]
	s_waitcnt vmcnt(0)
	v_pk_mul_f32 v[92:93], v[120:121], v[92:93]
	v_pk_mul_f32 v[94:95], v[122:123], v[94:95]
	v_pk_fma_f32 v[92:93], v[40:41], v[92:93], v[0:1]
	v_pk_fma_f32 v[94:95], v[42:43], v[94:95], v[2:3]
	v_cvt_pk_bf16_f32 v92, v92, v93
	v_cvt_pk_bf16_f32 v93, v94, v95
	global_store_dwordx2 v[126:127], v[92:93], off sc0 sc1
	v_pk_mul_f32 v[96:97], v[96:97], v[124:125] op_sel_hi:[1,0]
	v_pk_mul_f32 v[98:99], v[98:99], v[124:125] op_sel_hi:[1,0]
	v_pk_mul_f32 v[32:33], v[32:33], v[124:125] op_sel_hi:[1,0]
	v_pk_mul_f32 v[34:35], v[34:35], v[124:125] op_sel_hi:[1,0]
	v_cmp_lt_i32_e32 vcc, s7, v36
	s_or_b64 s[10:11], vcc, s[10:11]
	v_pk_mul_f32 v[92:93], v[180:181], v[96:97]
	v_pk_mul_f32 v[94:95], v[182:183], v[98:99]
	v_pk_fma_f32 v[92:93], v[44:45], v[92:93], v[4:5]
	v_pk_fma_f32 v[94:95], v[46:47], v[94:95], v[6:7]
	v_cvt_pk_bf16_f32 v92, v92, v93
	v_cvt_pk_bf16_f32 v93, v94, v95
	global_store_dwordx2 v[126:127], v[92:93], off offset:512 sc0 sc1
	v_pk_mul_f32 v[96:97], v[100:101], v[124:125] op_sel_hi:[1,0]
	v_pk_mul_f32 v[98:99], v[102:103], v[124:125] op_sel_hi:[1,0]
	v_pk_mul_f32 v[92:93], v[184:185], v[96:97]
	v_pk_mul_f32 v[94:95], v[186:187], v[98:99]
	v_pk_fma_f32 v[92:93], v[48:49], v[92:93], v[8:9]
	v_pk_fma_f32 v[94:95], v[50:51], v[94:95], v[10:11]
	v_cvt_pk_bf16_f32 v92, v92, v93
	v_cvt_pk_bf16_f32 v93, v94, v95
	global_store_dwordx2 v[126:127], v[92:93], off offset:1024 sc0 sc1
	v_pk_mul_f32 v[96:97], v[104:105], v[124:125] op_sel_hi:[1,0]
	v_pk_mul_f32 v[98:99], v[106:107], v[124:125] op_sel_hi:[1,0]
	v_pk_mul_f32 v[92:93], v[96:97], v[188:189]
	v_pk_mul_f32 v[94:95], v[98:99], v[190:191]
	v_pk_fma_f32 v[92:93], v[92:93], v[52:53], v[12:13]
	v_pk_fma_f32 v[94:95], v[94:95], v[54:55], v[14:15]
	v_cvt_pk_bf16_f32 v92, v92, v93
	v_cvt_pk_bf16_f32 v93, v94, v95
	global_store_dwordx2 v[126:127], v[92:93], off offset:1536 sc0 sc1
	v_pk_mul_f32 v[96:97], v[108:109], v[124:125] op_sel_hi:[1,0]
	v_pk_mul_f32 v[98:99], v[110:111], v[124:125] op_sel_hi:[1,0]
	v_pk_mul_f32 v[92:93], v[96:97], v[192:193]
	v_pk_mul_f32 v[94:95], v[98:99], v[194:195]
	v_pk_fma_f32 v[92:93], v[92:93], v[58:59], v[16:17]
	v_pk_fma_f32 v[94:95], v[94:95], v[60:61], v[18:19]
	v_cvt_pk_bf16_f32 v92, v92, v93
	v_cvt_pk_bf16_f32 v93, v94, v95
	global_store_dwordx2 v[126:127], v[92:93], off offset:2048 sc0 sc1
	v_pk_mul_f32 v[96:97], v[112:113], v[124:125] op_sel_hi:[1,0]
	v_pk_mul_f32 v[98:99], v[114:115], v[124:125] op_sel_hi:[1,0]
	v_pk_mul_f32 v[92:93], v[96:97], v[196:197]
	v_pk_mul_f32 v[94:95], v[98:99], v[198:199]
	v_pk_fma_f32 v[92:93], v[92:93], v[64:65], v[20:21]
	v_pk_fma_f32 v[94:95], v[94:95], v[66:67], v[22:23]
	v_cvt_pk_bf16_f32 v92, v92, v93
	v_cvt_pk_bf16_f32 v93, v94, v95
	global_store_dwordx2 v[126:127], v[92:93], off offset:2560 sc0 sc1
	v_pk_mul_f32 v[96:97], v[116:117], v[124:125] op_sel_hi:[1,0]
	v_pk_mul_f32 v[98:99], v[118:119], v[124:125] op_sel_hi:[1,0]
	v_pk_mul_f32 v[92:93], v[96:97], v[200:201]
	v_pk_mul_f32 v[94:95], v[98:99], v[202:203]
	v_pk_fma_f32 v[92:93], v[92:93], v[70:71], v[24:25]
	v_pk_fma_f32 v[94:95], v[94:95], v[72:73], v[26:27]
	v_cvt_pk_bf16_f32 v92, v92, v93
	v_cvt_pk_bf16_f32 v93, v94, v95
	global_store_dwordx2 v[126:127], v[92:93], off offset:3072 sc0 sc1
	v_pk_mul_f32 v[32:33], v[32:33], v[204:205]
	v_pk_mul_f32 v[34:35], v[34:35], v[206:207]
	v_pk_fma_f32 v[32:33], v[32:33], v[76:77], v[28:29]
	v_pk_fma_f32 v[34:35], v[34:35], v[78:79], v[30:31]
	v_cvt_pk_bf16_f32 v32, v32, v33
	v_cvt_pk_bf16_f32 v33, v34, v35
	global_store_dwordx2 v[126:127], v[32:33], off offset:3584 sc0 sc1
	s_andn2_b64 exec, exec, s[10:11]
	s_cbranch_execnz .LBB0_142

.LBB0_155:
	v_lshl_add_u32 v4, s0, 3, v125
	v_ashrrev_i32_e32 v5, 31, v4
	s_waitcnt vmcnt(0)
	v_lshlrev_b64 v[0:1], 13, v[4:5]
	v_lshl_add_u64 v[54:55], s[52:53], 0, v[0:1]
	v_lshlrev_b32_e32 v68, 2, v70
	v_lshl_add_u64 v[44:45], v[54:55], 0, v[68:69]
	global_load_dwordx4 v[0:3], v[44:45], off nt
	s_add_i32 s9, s0, 1
	s_cmp_ge_i32 s9, s6
	s_cselect_b64 s[14:15], -1, 0
	s_ashr_i32 s9, s9, 8
	s_cmp_lg_u32 s9, s7
	s_cselect_b64 s[16:17], -1, 0
	s_or_b64 s[16:17], s[14:15], s[16:17]
	v_lshlrev_b64 v[4:5], 12, v[4:5]
	v_lshl_add_u64 v[128:129], s[34:35], 0, v[4:5]
	s_mov_b64 s[14:15], -1
	s_and_b64 vcc, exec, s[16:17]
	v_lshlrev_b32_e32 v46, 2, v78
	v_lshlrev_b32_e32 v52, 2, v80
	v_lshlrev_b32_e32 v34, 2, v82
	v_lshlrev_b32_e32 v32, 2, v84
	v_lshlrev_b32_e32 v126, 1, v70
	s_cbranch_vccz .LBB0_157
	v_mov_b32_e32 v47, v69
	v_mov_b32_e32 v53, v69
	v_lshl_add_u64 v[4:5], v[54:55], 0, v[46:47]
	global_load_dwordx4 v[28:31], v[44:45], off offset:1024 nt
	global_load_dwordx4 v[24:27], v[44:45], off offset:2048 nt
	global_load_dwordx4 v[20:23], v[44:45], off offset:3072 nt
	v_lshl_add_u64 v[6:7], v[54:55], 0, v[52:53]
	global_load_dwordx4 v[16:19], v[4:5], off nt
	global_load_dwordx4 v[12:15], v[6:7], off nt
	v_mov_b32_e32 v35, v69
	v_mov_b32_e32 v33, v69
	v_lshl_add_u64 v[4:5], v[54:55], 0, v[34:35]
	v_lshl_add_u64 v[6:7], v[54:55], 0, v[32:33]
	global_load_dwordx4 v[8:11], v[4:5], off nt
	s_nop 0
	global_load_dwordx4 v[4:7], v[6:7], off nt
	v_and_b32_e32 v35, 64, v77
	global_load_dwordx4 v[36:39], v[114:115], off
	s_waitcnt vmcnt(8)
	v_mul_f32_e32 v33, v1, v1
	v_xor_b32_e32 v40, 32, v77
	v_add_u32_e32 v35, 64, v35
	v_fmac_f32_e32 v33, v0, v0
	v_cmp_lt_i32_e32 vcc, v40, v35
	v_fmac_f32_e32 v33, v2, v2
	v_fmac_f32_e32 v33, v3, v3
	v_cndmask_b32_e32 v40, v77, v40, vcc
	v_lshlrev_b32_e32 v53, 2, v40
	v_xor_b32_e32 v47, 16, v77
	v_cmp_lt_i32_e32 vcc, v47, v35
	v_mov_b32_e32 v127, v69
	s_add_i32 s7, s0, -1
	s_waitcnt vmcnt(7)
	v_mul_f32_e32 v64, v29, v29
	s_waitcnt vmcnt(6)
	v_mul_f32_e32 v65, v25, v25
	v_fmac_f32_e32 v64, v28, v28
	s_waitcnt vmcnt(5)
	v_mul_f32_e32 v66, v21, v21
	v_fmac_f32_e32 v65, v24, v24
	v_fmac_f32_e32 v64, v30, v30
	s_waitcnt vmcnt(4)
	v_mov_b32_e32 v42, v17
	s_waitcnt vmcnt(3)
	v_mov_b32_e32 v43, v13
	v_fmac_f32_e32 v66, v20, v20
	v_fmac_f32_e32 v65, v26, v26
	v_mov_b32_e32 v40, v16
	v_mov_b32_e32 v41, v12
	v_fmac_f32_e32 v64, v31, v31
	v_pk_mul_f32 v[42:43], v[42:43], v[42:43]
	v_fmac_f32_e32 v66, v22, v22
	v_mov_b32_e32 v48, v18
	v_mov_b32_e32 v49, v14
	s_waitcnt vmcnt(2)
	v_mov_b32_e32 v58, v9
	s_waitcnt vmcnt(1)
	v_mov_b32_e32 v59, v5
	v_fmac_f32_e32 v65, v27, v27
	v_add_f32_e32 v33, v33, v64
	v_pk_fma_f32 v[40:41], v[40:41], v[40:41], v[42:43]
	v_mov_b32_e32 v50, v19
	v_mov_b32_e32 v51, v15
	v_mov_b32_e32 v56, v8
	v_mov_b32_e32 v57, v4
	v_fmac_f32_e32 v66, v23, v23
	v_pk_mul_f32 v[58:59], v[58:59], v[58:59]
	v_add_f32_e32 v33, v33, v65
	v_pk_fma_f32 v[40:41], v[48:49], v[48:49], v[40:41]
	v_mov_b32_e32 v60, v10
	v_mov_b32_e32 v61, v6
	v_pk_fma_f32 v[42:43], v[56:57], v[56:57], v[58:59]
	v_add_f32_e32 v33, v33, v66
	v_pk_fma_f32 v[40:41], v[50:51], v[50:51], v[40:41]
	v_mov_b32_e32 v62, v11
	v_mov_b32_e32 v63, v7
	v_pk_fma_f32 v[42:43], v[60:61], v[60:61], v[42:43]
	v_add_f32_e32 v33, v33, v40
	v_pk_fma_f32 v[42:43], v[62:63], v[62:63], v[42:43]
	v_add_f32_e32 v33, v33, v41
	v_add_f32_e32 v33, v33, v42
	v_add_f32_e32 v33, v33, v43
	ds_bpermute_b32 v40, v53, v33
	v_cndmask_b32_e32 v42, v77, v47, vcc
	v_lshlrev_b32_e32 v42, 2, v42
	v_xor_b32_e32 v41, 8, v77
	v_cmp_lt_i32_e32 vcc, v41, v35
	s_waitcnt lgkmcnt(0)
	v_add_f32_e32 v33, v33, v40
	ds_bpermute_b32 v40, v42, v33
	v_cndmask_b32_e32 v41, v77, v41, vcc
	v_lshlrev_b32_e32 v41, 2, v41
	v_xor_b32_e32 v42, 4, v77
	v_cmp_lt_i32_e32 vcc, v42, v35
	s_waitcnt lgkmcnt(0)
	v_add_f32_e32 v33, v33, v40
	ds_bpermute_b32 v40, v41, v33
	v_cndmask_b32_e32 v42, v77, v42, vcc
	v_lshlrev_b32_e32 v42, 2, v42
	v_xor_b32_e32 v41, 2, v77
	v_cmp_lt_i32_e32 vcc, v41, v35
	s_waitcnt lgkmcnt(0)
	v_add_f32_e32 v33, v33, v40
	ds_bpermute_b32 v40, v42, v33
	v_cndmask_b32_e32 v41, v77, v41, vcc
	v_lshlrev_b32_e32 v41, 2, v41
	v_xor_b32_e32 v42, 1, v77
	v_cmp_lt_i32_e32 vcc, v42, v35
	s_waitcnt lgkmcnt(0)
	v_add_f32_e32 v33, v33, v40
	ds_bpermute_b32 v40, v41, v33
	v_cndmask_b32_e32 v35, v77, v42, vcc
	v_lshlrev_b32_e32 v35, 2, v35
	v_lshl_add_u64 v[64:65], v[128:129], 0, v[126:127]
	s_waitcnt lgkmcnt(0)
	v_add_f32_e32 v33, v33, v40
	ds_bpermute_b32 v35, v35, v33
	ds_read_b128 v[40:43], v73 offset:8192
	ds_read_b128 v[48:51], v73 offset:9216
	ds_read_b128 v[56:59], v73
	ds_read_b128 v[60:63], v73 offset:1024
	s_waitcnt lgkmcnt(3)
	v_pk_add_f32 v[40:41], v[40:41], 1.0 op_sel_hi:[1,0]
	v_pk_add_f32 v[42:43], v[42:43], 1.0 op_sel_hi:[1,0]
	v_add_f32_e32 v33, v33, v35
	v_fmamk_f32 v33, v33, 0x3a000000, v124
	v_mul_f32_e32 v35, 0x4b800000, v33
	v_cmp_gt_f32_e32 vcc, s1, v33
	s_nop 1
	v_cndmask_b32_e32 v33, v33, v35, vcc
	v_rsq_f32_e32 v33, v33
	s_nop 0
	v_mul_f32_e32 v35, 0x45800000, v33
	v_cndmask_b32_e32 v66, v33, v35, vcc
	v_pk_mul_f32 v[130:131], v[0:1], v[66:67] op_sel_hi:[1,0]
	v_pk_mul_f32 v[132:133], v[2:3], v[66:67] op_sel_hi:[1,0]
	s_waitcnt vmcnt(0)
	v_pk_mul_f32 v[36:37], v[36:37], v[130:131]
	v_pk_mul_f32 v[38:39], v[38:39], v[132:133]
	s_waitcnt lgkmcnt(1)
	v_pk_fma_f32 v[36:37], v[40:41], v[36:37], v[56:57]
	v_pk_fma_f32 v[38:39], v[42:43], v[38:39], v[58:59]
	v_cvt_pk_bf16_f32 v36, v36, v37
	v_cvt_pk_bf16_f32 v37, v38, v39
	global_store_dwordx2 v[64:65], v[36:37], off sc0 sc1
	v_pk_mul_f32 v[28:29], v[28:29], v[66:67] op_sel_hi:[1, 0]
	v_pk_mul_f32 v[30:31], v[30:31], v[66:67] op_sel_hi:[1, 0]
	v_pk_add_f32 v[40:41], v[48:49], 1.0 op_sel_hi:[1, 0]
	v_pk_add_f32 v[42:43], v[50:51], 1.0 op_sel_hi:[1, 0]
	v_pk_mul_f32 v[24:25], v[24:25], v[66:67] op_sel_hi:[1, 0]
	v_pk_mul_f32 v[26:27], v[26:27], v[66:67] op_sel_hi:[1, 0]
	v_pk_mul_f32 v[20:21], v[20:21], v[66:67] op_sel_hi:[1, 0]
	v_pk_mul_f32 v[22:23], v[22:23], v[66:67] op_sel_hi:[1, 0]
	v_pk_mul_f32 v[16:17], v[16:17], v[66:67] op_sel_hi:[1, 0]
	v_pk_mul_f32 v[18:19], v[18:19], v[66:67] op_sel_hi:[1, 0]
	v_pk_mul_f32 v[12:13], v[12:13], v[66:67] op_sel_hi:[1, 0]
	v_pk_mul_f32 v[14:15], v[14:15], v[66:67] op_sel_hi:[1, 0]
	v_pk_mul_f32 v[8:9], v[8:9], v[66:67] op_sel_hi:[1, 0]
	v_pk_mul_f32 v[10:11], v[10:11], v[66:67] op_sel_hi:[1, 0]
	v_pk_mul_f32 v[4:5], v[4:5], v[66:67] op_sel_hi:[1, 0]
	v_pk_mul_f32 v[6:7], v[6:7], v[66:67] op_sel_hi:[1, 0]
	s_waitcnt vmcnt(1)
	v_pk_mul_f32 v[28:29], v[184:185], v[28:29]
	v_pk_mul_f32 v[30:31], v[186:187], v[30:31]
	s_waitcnt lgkmcnt(0)
	v_pk_fma_f32 v[28:29], v[40:41], v[28:29], v[60:61]
	v_pk_fma_f32 v[30:31], v[42:43], v[30:31], v[62:63]
	v_cvt_pk_bf16_f32 v28, v28, v29
	v_cvt_pk_bf16_f32 v29, v30, v31
	global_store_dwordx2 v[64:65], v[28:29], off offset:512 sc0 sc1
	ds_read_b128 v[36:39], v73 offset:10240
	ds_read_b128 v[40:43], v73 offset:11264
	ds_read_b128 v[48:51], v73 offset:2048
	ds_read_b128 v[56:59], v73 offset:3072
	s_waitcnt lgkmcnt(3)
	v_pk_add_f32 v[36:37], v[36:37], 1.0 op_sel_hi:[1, 0]
	v_pk_add_f32 v[38:39], v[38:39], 1.0 op_sel_hi:[1, 0]
	s_waitcnt vmcnt(2)
	v_pk_mul_f32 v[24:25], v[188:189], v[24:25]
	v_pk_mul_f32 v[26:27], v[190:191], v[26:27]
	s_waitcnt lgkmcnt(1)
	v_pk_fma_f32 v[24:25], v[36:37], v[24:25], v[48:49]
	v_pk_fma_f32 v[26:27], v[38:39], v[26:27], v[50:51]
	v_cvt_pk_bf16_f32 v24, v24, v25
	v_cvt_pk_bf16_f32 v25, v26, v27
	global_store_dwordx2 v[64:65], v[24:25], off offset:1024 sc0 sc1
	v_pk_add_f32 v[28:29], v[40:41], 1.0 op_sel_hi:[1, 0]
	v_pk_add_f32 v[30:31], v[42:43], 1.0 op_sel_hi:[1, 0]
	s_waitcnt vmcnt(3)
	v_pk_mul_f32 v[20:21], v[20:21], v[192:193]
	v_pk_mul_f32 v[22:23], v[22:23], v[194:195]
	s_waitcnt lgkmcnt(0)
	v_pk_fma_f32 v[20:21], v[20:21], v[28:29], v[56:57]
	v_pk_fma_f32 v[22:23], v[22:23], v[30:31], v[58:59]
	v_cvt_pk_bf16_f32 v20, v20, v21
	v_cvt_pk_bf16_f32 v21, v22, v23
	global_store_dwordx2 v[64:65], v[20:21], off offset:1536 sc0 sc1
	ds_read_b128 v[24:27], v73 offset:12288
	ds_read_b128 v[28:31], v73 offset:13312
	ds_read_b128 v[36:39], v73 offset:4096
	ds_read_b128 v[40:43], v73 offset:5120
	s_waitcnt lgkmcnt(3)
	v_pk_add_f32 v[24:25], v[24:25], 1.0 op_sel_hi:[1, 0]
	v_pk_add_f32 v[26:27], v[26:27], 1.0 op_sel_hi:[1, 0]
	s_waitcnt vmcnt(4)
	v_pk_mul_f32 v[16:17], v[16:17], v[196:197]
	v_pk_mul_f32 v[18:19], v[18:19], v[198:199]
	s_waitcnt lgkmcnt(1)
	v_pk_fma_f32 v[16:17], v[16:17], v[24:25], v[36:37]
	v_pk_fma_f32 v[18:19], v[18:19], v[26:27], v[38:39]
	v_cvt_pk_bf16_f32 v16, v16, v17
	v_cvt_pk_bf16_f32 v17, v18, v19
	global_store_dwordx2 v[64:65], v[16:17], off offset:2048 sc0 sc1
	v_pk_add_f32 v[20:21], v[28:29], 1.0 op_sel_hi:[1, 0]
	v_pk_add_f32 v[22:23], v[30:31], 1.0 op_sel_hi:[1, 0]
	s_waitcnt vmcnt(5)
	v_pk_mul_f32 v[12:13], v[12:13], v[200:201]
	v_pk_mul_f32 v[14:15], v[14:15], v[202:203]
	s_waitcnt lgkmcnt(0)
	v_pk_fma_f32 v[12:13], v[12:13], v[20:21], v[40:41]
	v_pk_fma_f32 v[14:15], v[14:15], v[22:23], v[42:43]
	v_cvt_pk_bf16_f32 v12, v12, v13
	v_cvt_pk_bf16_f32 v13, v14, v15
	global_store_dwordx2 v[64:65], v[12:13], off offset:2560 sc0 sc1
	ds_read_b128 v[16:19], v73 offset:14336
	ds_read_b128 v[20:23], v73 offset:15360
	ds_read_b128 v[24:27], v73 offset:6144
	ds_read_b128 v[28:31], v73 offset:7168
	s_waitcnt lgkmcnt(3)
	v_pk_add_f32 v[16:17], v[16:17], 1.0 op_sel_hi:[1, 0]
	v_pk_add_f32 v[18:19], v[18:19], 1.0 op_sel_hi:[1, 0]
	s_waitcnt vmcnt(6)
	v_pk_mul_f32 v[8:9], v[8:9], v[204:205]
	v_pk_mul_f32 v[10:11], v[10:11], v[206:207]
	s_waitcnt lgkmcnt(1)
	v_pk_fma_f32 v[8:9], v[8:9], v[16:17], v[24:25]
	v_pk_fma_f32 v[10:11], v[10:11], v[18:19], v[26:27]
	v_cvt_pk_bf16_f32 v8, v8, v9
	v_cvt_pk_bf16_f32 v9, v10, v11
	global_store_dwordx2 v[64:65], v[8:9], off offset:3072 sc0 sc1
	v_pk_add_f32 v[12:13], v[20:21], 1.0 op_sel_hi:[1, 0]
	v_pk_add_f32 v[14:15], v[22:23], 1.0 op_sel_hi:[1, 0]
	s_waitcnt vmcnt(7)
	v_pk_mul_f32 v[4:5], v[4:5], v[208:209]
	v_pk_mul_f32 v[6:7], v[6:7], v[210:211]
	s_waitcnt lgkmcnt(0)
	v_pk_fma_f32 v[4:5], v[4:5], v[12:13], v[28:29]
	v_pk_fma_f32 v[6:7], v[6:7], v[14:15], v[30:31]
	v_cvt_pk_bf16_f32 v4, v4, v5
	v_cvt_pk_bf16_f32 v5, v6, v7
	global_store_dwordx2 v[64:65], v[4:5], off offset:3584 sc0 sc1
	s_cbranch_execnz .LBB0_152
	s_branch .LBB0_158

.LBB0_158:
	v_mov_b32_e32 v47, v69
	v_lshl_add_u64 v[4:5], v[54:55], 0, v[46:47]
	v_mov_b32_e32 v53, v69
	global_load_dwordx4 v[48:51], v[4:5], off nt
	v_lshl_add_u64 v[4:5], v[54:55], 0, v[52:53]
	v_mov_b32_e32 v35, v69
	global_load_dwordx4 v[40:43], v[4:5], off nt
	v_mov_b32_e32 v33, v69
	v_lshl_add_u64 v[4:5], v[54:55], 0, v[34:35]
	v_lshl_add_u64 v[130:131], v[54:55], 0, s[10:11]
	v_lshl_add_u64 v[6:7], v[54:55], 0, v[32:33]
	global_load_dwordx4 v[36:39], v[4:5], off nt
	global_load_dwordx4 v[28:31], v[6:7], off nt
	v_lshl_add_u64 v[4:5], v[130:131], 0, v[52:53]
	v_lshl_add_u64 v[8:9], v[130:131], 0, v[68:69]
	global_load_dwordx4 v[4:7], v[4:5], off nt
	v_lshlrev_b32_e32 v68, 2, v72
	global_load_dwordx4 v[24:27], v[8:9], off nt
	v_lshl_add_u64 v[8:9], v[130:131], 0, v[46:47]
	v_lshl_add_u64 v[12:13], v[130:131], 0, v[68:69]
	global_load_dwordx4 v[8:11], v[8:9], off nt
	s_nop 0
	global_load_dwordx4 v[20:23], v[12:13], off nt
	global_load_dwordx4 v[60:63], v[44:45], off offset:1024 nt
	v_lshlrev_b32_e32 v68, 2, v74
	v_lshl_add_u64 v[12:13], v[130:131], 0, v[68:69]
	global_load_dwordx4 v[16:19], v[12:13], off nt
	global_load_dwordx4 v[56:59], v[44:45], off offset:2048 nt
	global_load_dwordx4 v[52:55], v[44:45], off offset:3072 nt
	v_lshlrev_b32_e32 v68, 2, v76
	v_lshl_add_u64 v[12:13], v[130:131], 0, v[68:69]
	global_load_dwordx4 v[12:15], v[12:13], off nt
	v_and_b32_e32 v44, 64, v77
	v_lshl_add_u64 v[34:35], v[130:131], 0, v[34:35]
	v_lshl_add_u64 v[32:33], v[130:131], 0, v[32:33]
	global_load_dwordx4 v[64:67], v[114:115], off
	v_add_u32_e32 v81, 64, v44
	global_load_dwordx4 v[44:47], v[34:35], off nt
	s_nop 0
	global_load_dwordx4 v[32:35], v[32:33], off nt
	s_waitcnt vmcnt(16)
	v_mov_b32_e32 v135, v1
	v_mov_b32_e32 v133, v0
	v_mov_b32_e32 v137, v2
	v_mov_b32_e32 v139, v3
	v_xor_b32_e32 v68, 32, v77
	v_cmp_lt_i32_e32 vcc, v68, v81
	v_xor_b32_e32 v79, 16, v77
	v_mov_b32_e32 v127, v69
	v_cndmask_b32_e32 v68, v77, v68, vcc
	v_lshlrev_b32_e32 v68, 2, v68
	v_cmp_lt_i32_e32 vcc, v79, v81
	s_mov_b32 s7, s0
	s_waitcnt vmcnt(15)
	v_mov_b32_e32 v140, v49
	v_mov_b32_e32 v130, v48
	v_mov_b32_e32 v142, v50
	s_waitcnt vmcnt(14)
	v_mov_b32_e32 v141, v41
	v_mov_b32_e32 v131, v40
	v_pk_mul_f32 v[140:141], v[140:141], v[140:141]
	v_mov_b32_e32 v143, v42
	s_waitcnt vmcnt(13)
	v_mov_b32_e32 v150, v37
	s_waitcnt vmcnt(12)
	v_mov_b32_e32 v151, v29
	v_mov_b32_e32 v148, v36
	v_mov_b32_e32 v149, v28
	v_pk_mul_f32 v[150:151], v[150:151], v[150:151]
	v_mov_b32_e32 v152, v38
	s_waitcnt vmcnt(10)
	v_mov_b32_e32 v134, v25
	v_mov_b32_e32 v132, v24
	v_pk_mul_f32 v[134:135], v[134:135], v[134:135]
	v_mov_b32_e32 v153, v30
	v_mov_b32_e32 v136, v26
	v_pk_fma_f32 v[130:131], v[130:131], v[130:131], v[140:141]
	v_pk_fma_f32 v[140:141], v[148:149], v[148:149], v[150:151]
	v_pk_fma_f32 v[132:133], v[132:133], v[132:133], v[134:135]
	v_mov_b32_e32 v138, v27
	v_pk_fma_f32 v[134:135], v[152:153], v[152:153], v[140:141]
	v_pk_fma_f32 v[132:133], v[136:137], v[136:137], v[132:133]
	s_waitcnt vmcnt(8)
	v_mov_b32_e32 v140, v21
	s_waitcnt vmcnt(7)
	v_mov_b32_e32 v141, v61
	v_pk_fma_f32 v[132:133], v[138:139], v[138:139], v[132:133]
	v_mov_b32_e32 v138, v20
	v_mov_b32_e32 v139, v60
	v_pk_mul_f32 v[140:141], v[140:141], v[140:141]
	v_mov_b32_e32 v159, v5
	v_pk_fma_f32 v[138:139], v[138:139], v[138:139], v[140:141]
	v_mov_b32_e32 v140, v22
	v_mov_b32_e32 v141, v62
	v_pk_fma_f32 v[138:139], v[140:141], v[140:141], v[138:139]
	v_mov_b32_e32 v140, v23
	v_mov_b32_e32 v141, v63
	v_pk_fma_f32 v[138:139], v[140:141], v[140:141], v[138:139]
	s_waitcnt vmcnt(6)
	v_mov_b32_e32 v140, v17
	s_waitcnt vmcnt(5)
	v_mov_b32_e32 v141, v57
	v_pk_add_f32 v[132:133], v[132:133], v[138:139]
	v_mov_b32_e32 v138, v16
	v_mov_b32_e32 v139, v56
	v_pk_mul_f32 v[140:141], v[140:141], v[140:141]
	v_mov_b32_e32 v158, v9
	v_pk_fma_f32 v[138:139], v[138:139], v[138:139], v[140:141]
	v_mov_b32_e32 v140, v18
	v_mov_b32_e32 v141, v58
	v_pk_fma_f32 v[138:139], v[140:141], v[140:141], v[138:139]
	v_mov_b32_e32 v140, v19
	v_mov_b32_e32 v141, v59
	v_pk_fma_f32 v[138:139], v[140:141], v[140:141], v[138:139]
	s_waitcnt vmcnt(3)
	v_mov_b32_e32 v140, v13
	v_mov_b32_e32 v141, v53
	v_mov_b32_e32 v157, v4
	v_mov_b32_e32 v156, v8
	v_pk_mul_f32 v[136:137], v[158:159], v[158:159]
	v_pk_add_f32 v[132:133], v[132:133], v[138:139]
	v_mov_b32_e32 v138, v12
	v_mov_b32_e32 v139, v52
	v_pk_mul_f32 v[140:141], v[140:141], v[140:141]
	v_mov_b32_e32 v161, v6
	v_mov_b32_e32 v160, v10
	v_pk_fma_f32 v[136:137], v[156:157], v[156:157], v[136:137]
	v_pk_fma_f32 v[138:139], v[138:139], v[138:139], v[140:141]
	v_mov_b32_e32 v140, v14
	v_mov_b32_e32 v141, v54
	v_mov_b32_e32 v146, v51
	v_mov_b32_e32 v147, v43
	v_mov_b32_e32 v163, v7
	v_pk_fma_f32 v[130:131], v[142:143], v[142:143], v[130:131]
	v_mov_b32_e32 v162, v11
	v_pk_fma_f32 v[136:137], v[160:161], v[160:161], v[136:137]
	v_pk_fma_f32 v[138:139], v[140:141], v[140:141], v[138:139]
	v_mov_b32_e32 v140, v15
	v_mov_b32_e32 v141, v55
	v_pk_fma_f32 v[130:131], v[146:147], v[146:147], v[130:131]
	v_pk_fma_f32 v[136:137], v[162:163], v[162:163], v[136:137]
	v_pk_fma_f32 v[138:139], v[140:141], v[140:141], v[138:139]
	s_waitcnt vmcnt(1)
	v_mov_b32_e32 v140, v45
	v_pk_add_f32 v[132:133], v[132:133], v[138:139]
	v_mov_b32_e32 v138, v136
	v_mov_b32_e32 v139, v130
	s_waitcnt vmcnt(0)
	v_mov_b32_e32 v141, v33
	v_pk_add_f32 v[132:133], v[132:133], v[138:139]
	v_mov_b32_e32 v138, v44
	v_mov_b32_e32 v139, v32
	v_pk_mul_f32 v[140:141], v[140:141], v[140:141]
	v_mov_b32_e32 v154, v39
	v_pk_fma_f32 v[138:139], v[138:139], v[138:139], v[140:141]
	v_mov_b32_e32 v140, v46
	v_mov_b32_e32 v141, v34
	v_mov_b32_e32 v155, v31
	v_pk_fma_f32 v[138:139], v[140:141], v[140:141], v[138:139]
	v_mov_b32_e32 v140, v47
	v_mov_b32_e32 v141, v35
	v_pk_fma_f32 v[134:135], v[154:155], v[154:155], v[134:135]
	v_pk_fma_f32 v[138:139], v[140:141], v[140:141], v[138:139]
	v_mov_b32_e32 v130, v137
	v_pk_add_f32 v[130:131], v[132:133], v[130:131]
	v_mov_b32_e32 v132, v138
	v_mov_b32_e32 v133, v134
	v_pk_add_f32 v[130:131], v[130:131], v[132:133]
	v_mov_b32_e32 v134, v139
	v_pk_add_f32 v[130:131], v[130:131], v[134:135]
	ds_bpermute_b32 v133, v68, v131
	ds_bpermute_b32 v132, v68, v130
	v_cndmask_b32_e32 v68, v77, v79, vcc
	v_lshlrev_b32_e32 v68, 2, v68
	v_xor_b32_e32 v79, 8, v77
	v_cmp_lt_i32_e32 vcc, v79, v81
	s_waitcnt lgkmcnt(0)
	v_pk_add_f32 v[130:131], v[130:131], v[132:133]
	ds_bpermute_b32 v133, v68, v131
	ds_bpermute_b32 v132, v68, v130
	v_cndmask_b32_e32 v68, v77, v79, vcc
	v_lshlrev_b32_e32 v68, 2, v68
	v_xor_b32_e32 v79, 4, v77
	v_cmp_lt_i32_e32 vcc, v79, v81
	s_waitcnt lgkmcnt(0)
	v_pk_add_f32 v[130:131], v[130:131], v[132:133]
	ds_bpermute_b32 v133, v68, v131
	ds_bpermute_b32 v132, v68, v130
	v_cndmask_b32_e32 v68, v77, v79, vcc
	v_lshlrev_b32_e32 v68, 2, v68
	v_xor_b32_e32 v79, 2, v77
	v_cmp_lt_i32_e32 vcc, v79, v81
	s_waitcnt lgkmcnt(0)
	v_pk_add_f32 v[130:131], v[130:131], v[132:133]
	ds_bpermute_b32 v133, v68, v131
	ds_bpermute_b32 v132, v68, v130
	v_cndmask_b32_e32 v68, v77, v79, vcc
	v_lshlrev_b32_e32 v68, 2, v68
	v_xor_b32_e32 v79, 1, v77
	v_cmp_lt_i32_e32 vcc, v79, v81
	s_waitcnt lgkmcnt(0)
	v_pk_add_f32 v[134:135], v[130:131], v[132:133]
	ds_bpermute_b32 v137, v68, v135
	ds_bpermute_b32 v136, v68, v134
	v_cndmask_b32_e32 v68, v77, v79, vcc
	v_lshlrev_b32_e32 v68, 2, v68
	ds_read_b128 v[130:133], v73 offset:8192
	v_lshl_add_u64 v[154:155], v[128:129], 0, v[126:127]
	s_waitcnt lgkmcnt(1)
	v_pk_add_f32 v[138:139], v[134:135], v[136:137]
	ds_bpermute_b32 v141, v68, v139
	ds_bpermute_b32 v140, v68, v138
	ds_read_b128 v[134:137], v73 offset:9216
	s_waitcnt lgkmcnt(3)
	v_pk_add_f32 v[142:143], v[130:131], 1.0 op_sel_hi:[1,0]
	v_pk_add_f32 v[150:151], v[132:133], 1.0 op_sel_hi:[1,0]
	s_waitcnt lgkmcnt(1)
	v_pk_add_f32 v[130:131], v[138:139], v[140:141]
	s_nop 0
	v_pk_fma_f32 v[152:153], v[130:131], s[8:9], v[124:125] op_sel_hi:[1,0,0]
	ds_read_b128 v[130:133], v73
	ds_read_b128 v[138:141], v73 offset:1024
	v_mul_f32_e32 v68, 0x4b800000, v153
	v_cmp_gt_f32_e32 vcc, s1, v153
	s_waitcnt lgkmcnt(2)
	v_pk_add_f32 v[156:157], v[134:135], 1.0 op_sel_hi:[1,0]
	v_pk_add_f32 v[158:159], v[136:137], 1.0 op_sel_hi:[1,0]
	v_cndmask_b32_e32 v68, v153, v68, vcc
	v_rsq_f32_e32 v68, v68
	s_nop 0
	v_mul_f32_e32 v79, 0x45800000, v68
	v_cndmask_b32_e32 v68, v68, v79, vcc
	v_pk_mul_f32 v[0:1], v[0:1], v[68:69] op_sel_hi:[1,0]
	v_pk_mul_f32 v[2:3], v[2:3], v[68:69] op_sel_hi:[1,0]
	v_pk_mul_f32 v[0:1], v[64:65], v[0:1]
	v_pk_mul_f32 v[2:3], v[66:67], v[2:3]
	s_waitcnt lgkmcnt(1)
	v_pk_fma_f32 v[0:1], v[142:143], v[0:1], v[130:131]
	v_pk_fma_f32 v[2:3], v[150:151], v[2:3], v[132:133]
	v_cvt_pk_bf16_f32 v0, v0, v1
	v_cvt_pk_bf16_f32 v1, v2, v3
	global_store_dwordx2 v[154:155], v[0:1], off sc0 sc1
	v_pk_mul_f32 v[60:61], v[60:61], v[68:69] op_sel_hi:[1,0]
	v_pk_mul_f32 v[62:63], v[62:63], v[68:69] op_sel_hi:[1,0]
	v_pk_mul_f32 v[56:57], v[56:57], v[68:69] op_sel_hi:[1,0]
	v_pk_mul_f32 v[58:59], v[58:59], v[68:69] op_sel_hi:[1,0]
	v_pk_mul_f32 v[52:53], v[52:53], v[68:69] op_sel_hi:[1,0]
	v_pk_mul_f32 v[54:55], v[54:55], v[68:69] op_sel_hi:[1,0]
	v_pk_mul_f32 v[48:49], v[48:49], v[68:69] op_sel_hi:[1,0]
	v_pk_mul_f32 v[50:51], v[50:51], v[68:69] op_sel_hi:[1,0]
	v_pk_mul_f32 v[40:41], v[40:41], v[68:69] op_sel_hi:[1,0]
	v_pk_mul_f32 v[42:43], v[42:43], v[68:69] op_sel_hi:[1,0]
	v_pk_mul_f32 v[36:37], v[36:37], v[68:69] op_sel_hi:[1,0]
	v_pk_mul_f32 v[38:39], v[38:39], v[68:69] op_sel_hi:[1,0]
	v_pk_mul_f32 v[28:29], v[28:29], v[68:69] op_sel_hi:[1,0]
	v_pk_mul_f32 v[30:31], v[30:31], v[68:69] op_sel_hi:[1,0]
	v_cmp_gt_f32_e32 vcc, s1, v152
	v_lshlrev_b32_e32 v68, 1, v72
	v_pk_mul_f32 v[0:1], v[184:185], v[60:61]
	v_pk_mul_f32 v[2:3], v[186:187], v[62:63]
	s_waitcnt lgkmcnt(0)
	v_pk_fma_f32 v[0:1], v[156:157], v[0:1], v[138:139]
	v_pk_fma_f32 v[2:3], v[158:159], v[2:3], v[140:141]
	v_cvt_pk_bf16_f32 v0, v0, v1
	v_cvt_pk_bf16_f32 v1, v2, v3
	global_store_dwordx2 v[154:155], v[0:1], off offset:512 sc0 sc1
	ds_read_b128 v[60:63], v73 offset:10240
	ds_read_b128 v[64:67], v73 offset:11264
	ds_read_b128 v[134:137], v73 offset:2048
	ds_read_b128 v[146:149], v73 offset:3072
	s_waitcnt lgkmcnt(3)
	v_pk_add_f32 v[160:161], v[60:61], 1.0 op_sel_hi:[1,0]
	v_pk_add_f32 v[162:163], v[62:63], 1.0 op_sel_hi:[1,0]
	s_waitcnt lgkmcnt(2)
	v_pk_add_f32 v[164:165], v[64:65], 1.0 op_sel_hi:[1,0]
	v_pk_add_f32 v[166:167], v[66:67], 1.0 op_sel_hi:[1,0]
	v_pk_mul_f32 v[0:1], v[56:57], v[188:189]
	v_pk_mul_f32 v[2:3], v[58:59], v[190:191]
	s_waitcnt lgkmcnt(1)
	v_pk_fma_f32 v[0:1], v[0:1], v[160:161], v[134:135]
	v_pk_fma_f32 v[2:3], v[2:3], v[162:163], v[136:137]
	v_cvt_pk_bf16_f32 v0, v0, v1
	v_cvt_pk_bf16_f32 v1, v2, v3
	global_store_dwordx2 v[154:155], v[0:1], off offset:1024 sc0 sc1
	v_pk_mul_f32 v[0:1], v[52:53], v[192:193]
	v_pk_mul_f32 v[2:3], v[54:55], v[194:195]
	s_waitcnt lgkmcnt(0)
	v_pk_fma_f32 v[0:1], v[0:1], v[164:165], v[146:147]
	v_pk_fma_f32 v[2:3], v[2:3], v[166:167], v[148:149]
	v_cvt_pk_bf16_f32 v0, v0, v1
	v_cvt_pk_bf16_f32 v1, v2, v3
	global_store_dwordx2 v[154:155], v[0:1], off offset:1536 sc0 sc1
	ds_read_b128 v[52:55], v73 offset:12288
	ds_read_b128 v[56:59], v73 offset:13312
	ds_read_b128 v[60:63], v73 offset:4096
	ds_read_b128 v[64:67], v73 offset:5120
	s_waitcnt lgkmcnt(3)
	v_pk_add_f32 v[168:169], v[52:53], 1.0 op_sel_hi:[1,0]
	v_pk_add_f32 v[170:171], v[54:55], 1.0 op_sel_hi:[1,0]
	s_waitcnt lgkmcnt(2)
	v_pk_add_f32 v[172:173], v[56:57], 1.0 op_sel_hi:[1,0]
	v_pk_add_f32 v[174:175], v[58:59], 1.0 op_sel_hi:[1,0]
	v_pk_mul_f32 v[0:1], v[48:49], v[196:197]
	v_pk_mul_f32 v[2:3], v[50:51], v[198:199]
	s_waitcnt lgkmcnt(1)
	v_pk_fma_f32 v[0:1], v[0:1], v[168:169], v[60:61]
	v_pk_fma_f32 v[2:3], v[2:3], v[170:171], v[62:63]
	v_cvt_pk_bf16_f32 v0, v0, v1
	v_cvt_pk_bf16_f32 v1, v2, v3
	global_store_dwordx2 v[154:155], v[0:1], off offset:2048 sc0 sc1
	v_pk_mul_f32 v[0:1], v[40:41], v[200:201]
	v_pk_mul_f32 v[2:3], v[42:43], v[202:203]
	s_waitcnt lgkmcnt(0)
	v_pk_fma_f32 v[0:1], v[0:1], v[172:173], v[64:65]
	v_pk_fma_f32 v[2:3], v[2:3], v[174:175], v[66:67]
	v_cvt_pk_bf16_f32 v0, v0, v1
	v_cvt_pk_bf16_f32 v1, v2, v3
	global_store_dwordx2 v[154:155], v[0:1], off offset:2560 sc0 sc1
	ds_read_b128 v[40:43], v73 offset:14336
	ds_read_b128 v[48:51], v73 offset:15360
	ds_read_b128 v[52:55], v73 offset:6144
	ds_read_b128 v[56:59], v73 offset:7168
	s_waitcnt lgkmcnt(3)
	v_pk_add_f32 v[40:41], v[40:41], 1.0 op_sel_hi:[1,0]
	v_pk_add_f32 v[42:43], v[42:43], 1.0 op_sel_hi:[1,0]
	v_pk_mul_f32 v[0:1], v[36:37], v[204:205]
	v_pk_mul_f32 v[2:3], v[38:39], v[206:207]
	s_waitcnt lgkmcnt(1)
	v_pk_fma_f32 v[0:1], v[0:1], v[40:41], v[52:53]
	v_pk_fma_f32 v[2:3], v[2:3], v[42:43], v[54:55]
	v_cvt_pk_bf16_f32 v0, v0, v1
	v_cvt_pk_bf16_f32 v1, v2, v3
	global_store_dwordx2 v[154:155], v[0:1], off offset:3072 sc0 sc1
	v_pk_add_f32 v[36:37], v[48:49], 1.0 op_sel_hi:[1,0]
	v_pk_add_f32 v[38:39], v[50:51], 1.0 op_sel_hi:[1,0]
	v_pk_mul_f32 v[0:1], v[28:29], v[208:209]
	v_pk_mul_f32 v[2:3], v[30:31], v[210:211]
	s_waitcnt lgkmcnt(0)
	v_pk_fma_f32 v[0:1], v[0:1], v[36:37], v[56:57]
	v_pk_fma_f32 v[2:3], v[2:3], v[38:39], v[58:59]
	v_cvt_pk_bf16_f32 v0, v0, v1
	v_cvt_pk_bf16_f32 v1, v2, v3
	global_store_dwordx2 v[154:155], v[0:1], off offset:3584 sc0 sc1
	v_mul_f32_e32 v28, 0x4b800000, v152
	v_cndmask_b32_e32 v28, v152, v28, vcc
	v_rsq_f32_e32 v48, v28
	v_lshl_add_u64 v[28:29], v[128:129], 0, s[12:13]
	v_lshl_add_u64 v[30:31], v[28:29], 0, v[126:127]
	v_mul_f32_e32 v49, 0x45800000, v48
	v_cndmask_b32_e32 v48, v48, v49, vcc
	v_pk_mul_f32 v[24:25], v[24:25], v[48:49] op_sel_hi:[1,0]
	v_pk_mul_f32 v[26:27], v[26:27], v[48:49] op_sel_hi:[1,0]
	v_pk_mul_f32 v[20:21], v[20:21], v[48:49] op_sel_hi:[1,0]
	v_pk_mul_f32 v[22:23], v[22:23], v[48:49] op_sel_hi:[1,0]
	v_pk_mul_f32 v[16:17], v[16:17], v[48:49] op_sel_hi:[1,0]
	v_pk_mul_f32 v[18:19], v[18:19], v[48:49] op_sel_hi:[1,0]
	v_pk_mul_f32 v[12:13], v[12:13], v[48:49] op_sel_hi:[1,0]
	v_pk_mul_f32 v[14:15], v[14:15], v[48:49] op_sel_hi:[1,0]
	v_pk_mul_f32 v[8:9], v[8:9], v[48:49] op_sel_hi:[1,0]
	v_pk_mul_f32 v[10:11], v[10:11], v[48:49] op_sel_hi:[1,0]
	v_pk_mul_f32 v[4:5], v[4:5], v[48:49] op_sel_hi:[1,0]
	v_pk_mul_f32 v[6:7], v[6:7], v[48:49] op_sel_hi:[1,0]
	v_pk_mul_f32 v[0:1], v[180:181], v[24:25]
	v_pk_mul_f32 v[2:3], v[182:183], v[26:27]
	v_pk_fma_f32 v[0:1], v[142:143], v[0:1], v[130:131]
	v_pk_fma_f32 v[2:3], v[150:151], v[2:3], v[132:133]
	v_cvt_pk_bf16_f32 v0, v0, v1
	v_cvt_pk_bf16_f32 v1, v2, v3
	global_store_dwordx2 v[30:31], v[0:1], off sc0 sc1
	v_lshl_add_u64 v[24:25], v[28:29], 0, v[68:69]
	v_lshlrev_b32_e32 v68, 1, v74
	v_pk_mul_f32 v[0:1], v[184:185], v[20:21]
	v_pk_mul_f32 v[2:3], v[186:187], v[22:23]
	v_pk_fma_f32 v[0:1], v[156:157], v[0:1], v[138:139]
	v_pk_fma_f32 v[2:3], v[158:159], v[2:3], v[140:141]
	v_cvt_pk_bf16_f32 v0, v0, v1
	v_cvt_pk_bf16_f32 v1, v2, v3
	global_store_dwordx2 v[24:25], v[0:1], off sc0 sc1
	v_lshl_add_u64 v[20:21], v[28:29], 0, v[68:69]
	v_lshlrev_b32_e32 v68, 1, v76
	v_pk_mul_f32 v[0:1], v[188:189], v[16:17]
	v_pk_mul_f32 v[2:3], v[190:191], v[18:19]
	v_pk_fma_f32 v[0:1], v[160:161], v[0:1], v[134:135]
	v_pk_fma_f32 v[2:3], v[162:163], v[2:3], v[136:137]
	v_cvt_pk_bf16_f32 v0, v0, v1
	v_cvt_pk_bf16_f32 v1, v2, v3
	global_store_dwordx2 v[20:21], v[0:1], off sc0 sc1
	v_lshl_add_u64 v[16:17], v[28:29], 0, v[68:69]
	v_lshlrev_b32_e32 v68, 1, v78
	v_pk_mul_f32 v[0:1], v[192:193], v[12:13]
	v_pk_mul_f32 v[2:3], v[194:195], v[14:15]
	v_pk_fma_f32 v[0:1], v[164:165], v[0:1], v[146:147]
	v_pk_fma_f32 v[2:3], v[166:167], v[2:3], v[148:149]
	v_cvt_pk_bf16_f32 v0, v0, v1
	v_cvt_pk_bf16_f32 v1, v2, v3
	global_store_dwordx2 v[16:17], v[0:1], off sc0 sc1
	v_lshl_add_u64 v[12:13], v[28:29], 0, v[68:69]
	v_lshlrev_b32_e32 v68, 1, v80
	v_pk_mul_f32 v[0:1], v[8:9], v[196:197]
	v_pk_mul_f32 v[2:3], v[10:11], v[198:199]
	v_pk_fma_f32 v[0:1], v[168:169], v[0:1], v[60:61]
	v_pk_fma_f32 v[2:3], v[170:171], v[2:3], v[62:63]
	v_cvt_pk_bf16_f32 v0, v0, v1
	v_cvt_pk_bf16_f32 v1, v2, v3
	global_store_dwordx2 v[12:13], v[0:1], off sc0 sc1
	v_lshl_add_u64 v[8:9], v[28:29], 0, v[68:69]
	v_lshlrev_b32_e32 v68, 1, v82
	v_pk_mul_f32 v[0:1], v[4:5], v[200:201]
	v_pk_mul_f32 v[2:3], v[6:7], v[202:203]
	v_pk_fma_f32 v[0:1], v[172:173], v[0:1], v[64:65]
	v_pk_fma_f32 v[2:3], v[174:175], v[2:3], v[66:67]
	v_cvt_pk_bf16_f32 v0, v0, v1
	v_cvt_pk_bf16_f32 v1, v2, v3
	global_store_dwordx2 v[8:9], v[0:1], off sc0 sc1
	v_pk_mul_f32 v[6:7], v[44:45], v[48:49] op_sel_hi:[1,0]
	v_pk_mul_f32 v[8:9], v[46:47], v[48:49] op_sel_hi:[1,0]
	v_lshl_add_u64 v[4:5], v[28:29], 0, v[68:69]
	v_lshlrev_b32_e32 v68, 1, v84
	v_pk_mul_f32 v[0:1], v[6:7], v[204:205]
	v_pk_mul_f32 v[2:3], v[8:9], v[206:207]
	v_pk_fma_f32 v[0:1], v[40:41], v[0:1], v[52:53]
	v_pk_fma_f32 v[2:3], v[42:43], v[2:3], v[54:55]
	v_cvt_pk_bf16_f32 v0, v0, v1
	v_cvt_pk_bf16_f32 v1, v2, v3
	global_store_dwordx2 v[4:5], v[0:1], off sc0 sc1
	v_pk_mul_f32 v[6:7], v[32:33], v[48:49] op_sel_hi:[1,0]
	v_pk_mul_f32 v[8:9], v[34:35], v[48:49] op_sel_hi:[1,0]
	v_lshl_add_u64 v[4:5], v[28:29], 0, v[68:69]
	v_pk_mul_f32 v[0:1], v[6:7], v[208:209]
	v_pk_mul_f32 v[2:3], v[8:9], v[210:211]
	v_pk_fma_f32 v[0:1], v[36:37], v[0:1], v[56:57]
	v_pk_fma_f32 v[2:3], v[38:39], v[2:3], v[58:59]
	v_cvt_pk_bf16_f32 v0, v0, v1
	v_cvt_pk_bf16_f32 v1, v2, v3
	global_store_dwordx2 v[4:5], v[0:1], off sc0 sc1
	s_branch .LBB0_152
